# out-projection epilogue: final rows staged through an LDS image, global stores are contiguous 1 KiB per instruction; fw loads hoisted
# speedup vs baseline: 1.0166x; 1.0079x over previous
.LBB0_923:
	s_barrier
	s_lshl_b32 s1, s18, 8
	v_readfirstlane_b32 s7, v0
	s_ashr_i32 s2, s7, 6
	s_mov_b32 s87, s2
	s_and_b32 s0, s2, 3
	s_lshl_b32 s3, s0, 5
	s_or_b32 s1, s3, s1
	v_lshrrev_b32_e32 v130, 2, v0
	v_and_or_b32 v130, v130, 12, s1
	v_mov_b32_e32 v147, 0
	v_lshlrev_b32_e32 v146, 2, v130
	v_lshl_add_u64 v[130:131], s[82:83], 0, v[146:147]
	s_mov_b64 s[4:5], 0xb40000
	v_lshl_add_u64 v[142:143], v[130:131], 0, s[4:5]
	v_and_b32_e32 v167, 15, v0
	s_ashr_i32 s4, s7, 8
	v_lshl_or_b32 v166, s4, 6, v167
	s_lshl_b32 s3, s6, 8
	v_add_u32_e32 v148, s3, v166
	v_readlane_b32 s36, v254, 8
	v_ashrrev_i32_e32 v149, 31, v148
	v_readlane_b32 s37, v254, 9
	s_mov_b32 s1, 0xb40000
	v_lshlrev_b64 v[134:135], 12, v[148:149]
	s_mov_b64 s[12:13], s[36:37]
	v_add_co_u32_e32 v130, vcc, s1, v130
	v_lshl_add_u64 v[134:135], s[12:13], 0, v[134:135]
	s_nop 0
	v_addc_co_u32_e32 v131, vcc, 0, v131, vcc
	v_lshl_add_u64 v[144:145], v[134:135], 0, v[146:147]
	global_load_dwordx4 v[130:133], v[130:131], off
	s_nop 0
	global_load_dwordx4 v[152:155], v[144:145], off
	global_load_dwordx4 v[156:159], v[144:145], off offset:64
	global_load_dwordx4 v[138:141], v[142:143], off offset:64
	global_load_dwordx4 v[134:137], v[142:143], off offset:512
	global_load_dwordx4 v[160:163], v[144:145], off offset:512
	global_load_dwordx4 v[168:171], v[144:145], off offset:576
	s_nop 0
	global_load_dwordx4 v[142:145], v[142:143], off offset:576
	v_or_b32_e32 v150, 16, v148
	v_ashrrev_i32_e32 v151, 31, v150
	v_lshlrev_b64 v[172:173], 12, v[150:151]
	v_lshl_add_u64 v[172:173], s[12:13], 0, v[172:173]
	v_lshl_add_u64 v[172:173], v[172:173], 0, v[146:147]
	v_mbcnt_hi_u32_b32 v198, -1, v1
	v_xor_b32_e32 v1, 16, v198
	s_lshl_b32 s0, s0, 3
	s_add_i32 s5, s0, 0
	v_readlane_b32 s38, v254, 10
	v_readlane_b32 s39, v254, 11
	v_readlane_b32 s40, v254, 12
	v_readlane_b32 s41, v254, 13
	v_readlane_b32 s42, v254, 14
	v_readlane_b32 s43, v254, 15
	v_readlane_b32 s44, v254, 16
	v_readlane_b32 s45, v254, 17
	v_readlane_b32 s46, v254, 18
	v_readlane_b32 s47, v254, 19
	v_readlane_b32 s48, v254, 20
	v_readlane_b32 s49, v254, 21
	v_readlane_b32 s50, v254, 22
	v_readlane_b32 s51, v254, 23
	s_waitcnt vmcnt(0)
	v_pk_fma_f32 v[40:41], v[40:41], v[140:141], v[158:159]
	v_pk_fma_f32 v[38:39], v[38:39], v[138:139], v[156:157]
	v_pk_fma_f32 v[16:17], v[16:17], v[136:137], v[162:163]
	v_pk_fma_f32 v[68:69], v[68:69], v[132:133], v[154:155]
	v_pk_fma_f32 v[66:67], v[66:67], v[130:131], v[152:153]
	v_pk_fma_f32 v[14:15], v[14:15], v[134:135], v[160:161]
	v_pk_fma_f32 v[4:5], v[4:5], v[144:145], v[170:171]
	v_pk_fma_f32 v[2:3], v[2:3], v[142:143], v[168:169]
	v_or_b32_e32 v152, 32, v148
	global_load_dwordx4 v[154:157], v[172:173], off
	global_load_dwordx4 v[158:161], v[172:173], off offset:64
	global_load_dwordx4 v[168:171], v[172:173], off offset:512
	s_nop 0
	global_load_dwordx4 v[172:175], v[172:173], off offset:576
	v_ashrrev_i32_e32 v153, 31, v152
	v_lshlrev_b64 v[162:163], 12, v[152:153]
	v_lshl_add_u64 v[162:163], s[12:13], 0, v[162:163]
	v_lshl_add_u64 v[176:177], v[162:163], 0, v[146:147]
	v_mov_b32_e32 v188, v67
	v_mov_b32_e32 v189, v68
	v_mov_b32_e32 v190, v66
	v_mov_b32_e32 v191, v69
	v_mov_b32_e32 v192, v39
	v_mov_b32_e32 v193, v40
	v_pk_add_f32 v[188:189], v[188:189], v[190:191]
	v_add_f32_e32 v195, v16, v17
	v_mov_b32_e32 v194, v3
	v_mov_b32_e32 v196, v5
	s_waitcnt vmcnt(3)
	v_pk_fma_f32 v[80:81], v[80:81], v[132:133], v[156:157]
	v_pk_fma_f32 v[78:79], v[78:79], v[130:131], v[154:155]
	s_waitcnt vmcnt(2)
	v_pk_fma_f32 v[48:49], v[48:49], v[140:141], v[160:161]
	v_pk_fma_f32 v[46:47], v[46:47], v[138:139], v[158:159]
	s_waitcnt vmcnt(1)
	v_pk_fma_f32 v[24:25], v[24:25], v[136:137], v[170:171]
	v_pk_fma_f32 v[22:23], v[22:23], v[134:135], v[168:169]
	s_waitcnt vmcnt(0)
	v_pk_fma_f32 v[8:9], v[8:9], v[144:145], v[174:175]
	v_pk_fma_f32 v[6:7], v[6:7], v[142:143], v[172:173]
	v_or_b32_e32 v154, 48, v148
	global_load_dwordx4 v[156:159], v[176:177], off
	global_load_dwordx4 v[160:163], v[176:177], off offset:64
	global_load_dwordx4 v[168:171], v[176:177], off offset:512
	global_load_dwordx4 v[172:175], v[176:177], off offset:576
	v_ashrrev_i32_e32 v155, 31, v154
	v_lshlrev_b64 v[176:177], 12, v[154:155]
	v_lshl_add_u64 v[176:177], s[12:13], 0, v[176:177]
	v_lshl_add_u64 v[176:177], v[176:177], 0, v[146:147]
	s_waitcnt vmcnt(3)
	v_pk_fma_f32 v[92:93], v[92:93], v[132:133], v[158:159]
	v_pk_fma_f32 v[90:91], v[90:91], v[130:131], v[156:157]
	s_waitcnt vmcnt(2)
	v_pk_fma_f32 v[60:61], v[60:61], v[140:141], v[162:163]
	v_pk_fma_f32 v[58:59], v[58:59], v[138:139], v[160:161]
	s_waitcnt vmcnt(1)
	v_pk_fma_f32 v[32:33], v[32:33], v[136:137], v[170:171]
	v_pk_fma_f32 v[30:31], v[30:31], v[134:135], v[168:169]
	s_waitcnt vmcnt(0)
	v_pk_fma_f32 v[12:13], v[12:13], v[144:145], v[174:175]
	v_pk_fma_f32 v[10:11], v[10:11], v[142:143], v[172:173]
	v_add_u32_e32 v156, 0x80, v148
	global_load_dwordx4 v[158:161], v[176:177], off
	global_load_dwordx4 v[168:171], v[176:177], off offset:64
	global_load_dwordx4 v[172:175], v[176:177], off offset:512
	s_nop 0
	global_load_dwordx4 v[176:179], v[176:177], off offset:576
	v_ashrrev_i32_e32 v157, 31, v156
	v_lshlrev_b64 v[162:163], 12, v[156:157]
	v_lshl_add_u64 v[162:163], s[12:13], 0, v[162:163]
	v_lshl_add_u64 v[180:181], v[162:163], 0, v[146:147]
	s_waitcnt vmcnt(3)
	v_pk_fma_f32 v[104:105], v[104:105], v[132:133], v[160:161]
	v_pk_fma_f32 v[102:103], v[102:103], v[130:131], v[158:159]
	s_waitcnt vmcnt(2)
	v_pk_fma_f32 v[72:73], v[72:73], v[140:141], v[170:171]
	v_pk_fma_f32 v[70:71], v[70:71], v[138:139], v[168:169]
	s_waitcnt vmcnt(1)
	v_pk_fma_f32 v[44:45], v[44:45], v[136:137], v[174:175]
	v_pk_fma_f32 v[42:43], v[42:43], v[134:135], v[172:173]
	s_waitcnt vmcnt(0)
	v_pk_fma_f32 v[20:21], v[20:21], v[144:145], v[178:179]
	v_pk_fma_f32 v[18:19], v[18:19], v[142:143], v[176:177]
	v_add_u32_e32 v158, 0x90, v148
	global_load_dwordx4 v[160:163], v[180:181], off
	global_load_dwordx4 v[168:171], v[180:181], off offset:64
	global_load_dwordx4 v[172:175], v[180:181], off offset:512
	global_load_dwordx4 v[176:179], v[180:181], off offset:576
	v_ashrrev_i32_e32 v159, 31, v158
	v_lshlrev_b64 v[180:181], 12, v[158:159]
	v_lshl_add_u64 v[180:181], s[12:13], 0, v[180:181]
	v_lshl_add_u64 v[180:181], v[180:181], 0, v[146:147]
	s_waitcnt vmcnt(3)
	v_pk_fma_f32 v[108:109], v[108:109], v[132:133], v[162:163]
	v_pk_fma_f32 v[106:107], v[106:107], v[130:131], v[160:161]
	s_waitcnt vmcnt(2)
	v_pk_fma_f32 v[84:85], v[84:85], v[140:141], v[170:171]
	v_pk_fma_f32 v[82:83], v[82:83], v[138:139], v[168:169]
	s_waitcnt vmcnt(1)
	v_pk_fma_f32 v[52:53], v[52:53], v[136:137], v[174:175]
	v_pk_fma_f32 v[50:51], v[50:51], v[134:135], v[172:173]
	s_waitcnt vmcnt(0)
	v_pk_fma_f32 v[28:29], v[28:29], v[144:145], v[178:179]
	v_pk_fma_f32 v[26:27], v[26:27], v[142:143], v[176:177]
	v_add_u32_e32 v160, 0xa0, v148
	global_load_dwordx4 v[168:171], v[180:181], off
	global_load_dwordx4 v[172:175], v[180:181], off offset:64
	global_load_dwordx4 v[176:179], v[180:181], off offset:512
	s_nop 0
	global_load_dwordx4 v[180:183], v[180:181], off offset:576
	v_ashrrev_i32_e32 v161, 31, v160
	v_lshlrev_b64 v[162:163], 12, v[160:161]
	v_lshl_add_u64 v[162:163], s[12:13], 0, v[162:163]
	v_lshl_add_u64 v[162:163], v[162:163], 0, v[146:147]
	s_waitcnt vmcnt(3)
	v_pk_fma_f32 v[120:121], v[120:121], v[132:133], v[170:171]
	v_pk_fma_f32 v[118:119], v[118:119], v[130:131], v[168:169]
	s_waitcnt vmcnt(2)
	v_pk_fma_f32 v[96:97], v[96:97], v[140:141], v[174:175]
	v_pk_fma_f32 v[94:95], v[94:95], v[138:139], v[172:173]
	s_waitcnt vmcnt(1)
	v_pk_fma_f32 v[64:65], v[64:65], v[136:137], v[178:179]
	v_pk_fma_f32 v[62:63], v[62:63], v[134:135], v[176:177]
	s_waitcnt vmcnt(0)
	v_pk_fma_f32 v[36:37], v[36:37], v[144:145], v[182:183]
	v_pk_fma_f32 v[34:35], v[34:35], v[142:143], v[180:181]
	s_nop 0
	global_load_dwordx4 v[168:171], v[162:163], off
	global_load_dwordx4 v[172:175], v[162:163], off offset:64
	global_load_dwordx4 v[176:179], v[162:163], off offset:512
	global_load_dwordx4 v[180:183], v[162:163], off offset:576
	v_and_b32_e32 v162, 64, v198
	v_add_u32_e32 v199, 64, v162
	v_add_u32_e32 v162, 0xb0, v148
	v_ashrrev_i32_e32 v163, 31, v162
	v_lshlrev_b64 v[184:185], 12, v[162:163]
	v_lshl_add_u64 v[184:185], s[12:13], 0, v[184:185]
	v_lshl_add_u64 v[184:185], v[184:185], 0, v[146:147]
	v_add_f32_e32 v147, v188, v189
	v_add_f32_e32 v197, 0, v147
	v_cmp_lt_i32_e32 vcc, v1, v199
	s_waitcnt vmcnt(3)
	v_pk_fma_f32 v[128:129], v[128:129], v[132:133], v[170:171]
	v_pk_fma_f32 v[126:127], v[126:127], v[130:131], v[168:169]
	s_waitcnt vmcnt(2)
	v_pk_fma_f32 v[112:113], v[112:113], v[140:141], v[174:175]
	v_pk_fma_f32 v[110:111], v[110:111], v[138:139], v[172:173]
	s_waitcnt vmcnt(1)
	v_pk_fma_f32 v[88:89], v[88:89], v[136:137], v[178:179]
	v_pk_fma_f32 v[86:87], v[86:87], v[134:135], v[176:177]
	s_waitcnt vmcnt(0)
	v_pk_fma_f32 v[56:57], v[56:57], v[144:145], v[182:183]
	v_pk_fma_f32 v[54:55], v[54:55], v[142:143], v[180:181]
	v_mov_b32_e32 v168, v38
	global_load_dwordx4 v[172:175], v[184:185], off
	global_load_dwordx4 v[176:179], v[184:185], off offset:64
	global_load_dwordx4 v[180:183], v[184:185], off offset:512
	v_mov_b32_e32 v169, v41
	global_load_dwordx4 v[184:187], v[184:185], off offset:576
	v_pk_add_f32 v[168:169], v[192:193], v[168:169]
	v_add_f32_e32 v171, v14, v15
	v_pk_add_f32 v[168:169], v[168:169], v[168:169] op_sel_hi:[0,1]
	v_mov_b32_e32 v170, v2
	v_mov_b32_e32 v168, v4
	v_pk_add_f32 v[170:171], v[170:171], v[194:195]
	v_pk_add_f32 v[168:169], v[168:169], v[196:197]
	v_cndmask_b32_e32 v1, v198, v1, vcc
	v_pk_add_f32 v[168:169], v[170:171], v[168:169]
	v_lshlrev_b32_e32 v1, 2, v1
	v_add_f32_e32 v147, v168, v169
	ds_bpermute_b32 v169, v1, v147
	v_xor_b32_e32 v168, 32, v198
	v_cmp_lt_i32_e32 vcc, v168, v199
	s_waitcnt lgkmcnt(0)
	v_add_f32_e32 v147, v147, v169
	v_cndmask_b32_e32 v168, v198, v168, vcc
	v_lshlrev_b32_e32 v168, 2, v168
	ds_bpermute_b32 v169, v168, v147
	s_waitcnt lgkmcnt(0)
	v_add_f32_e32 v169, v147, v169
	v_fmamk_f32 v170, v169, 0xbc800000, v69
	v_fmamk_f32 v188, v169, 0xbc800000, v67
	v_fmamk_f32 v190, v169, 0xbc800000, v41
	v_fmamk_f32 v192, v169, 0xbc800000, v39
	v_fmamk_f32 v147, v169, 0xbc800000, v68
	v_fmamk_f32 v171, v169, 0xbc800000, v66
	v_fmamk_f32 v189, v169, 0xbc800000, v40
	v_fmamk_f32 v191, v169, 0xbc800000, v38
	v_fmamk_f32 v194, v169, 0xbc800000, v17
	v_fmamk_f32 v196, v169, 0xbc800000, v15
	v_mul_f32_e32 v188, v188, v188
	v_mul_f32_e32 v170, v170, v170
	v_mul_f32_e32 v192, v192, v192
	v_mul_f32_e32 v190, v190, v190
	v_fmamk_f32 v193, v169, 0xbc800000, v16
	v_fmamk_f32 v195, v169, 0xbc800000, v14
	v_fmamk_f32 v198, v169, 0xbc800000, v5
	v_fmamk_f32 v200, v169, 0xbc800000, v3
	v_mul_f32_e32 v196, v196, v196
	v_mul_f32_e32 v194, v194, v194
	v_fmac_f32_e32 v188, v171, v171
	v_fmac_f32_e32 v170, v147, v147
	v_fmac_f32_e32 v192, v191, v191
	v_fmac_f32_e32 v190, v189, v189
	v_fmamk_f32 v197, v169, 0xbc800000, v4
	v_fmamk_f32 v199, v169, 0xbc800000, v2
	v_mul_f32_e32 v200, v200, v200
	v_mul_f32_e32 v198, v198, v198
	v_fmac_f32_e32 v196, v195, v195
	v_fmac_f32_e32 v194, v193, v193
	v_add_f32_e32 v147, v188, v170
	v_add_f32_e32 v170, v192, v190
	v_fmac_f32_e32 v200, v199, v199
	v_fmac_f32_e32 v198, v197, v197
	v_add_f32_e32 v171, v196, v194
	v_add_f32_e32 v147, v147, v170
	v_add_f32_e32 v188, v200, v198
	v_add_f32_e32 v147, v171, v147
	v_add_f32_e32 v170, v188, v147
	ds_bpermute_b32 v171, v1, v170
	v_and_b32_e32 v147, 63, v0
	v_cmp_gt_u32_e32 vcc, 16, v147
	s_waitcnt lgkmcnt(0)
	v_add_f32_e32 v170, v170, v171
	ds_bpermute_b32 v171, v168, v170
	s_waitcnt vmcnt(3)
	v_pk_fma_f32 v[124:125], v[124:125], v[132:133], v[174:175]
	v_pk_fma_f32 v[122:123], v[122:123], v[130:131], v[172:173]
	s_waitcnt vmcnt(2)
	v_pk_fma_f32 v[116:117], v[116:117], v[140:141], v[178:179]
	v_pk_fma_f32 v[114:115], v[114:115], v[138:139], v[176:177]
	s_waitcnt vmcnt(1)
	v_pk_fma_f32 v[100:101], v[100:101], v[136:137], v[182:183]
	v_pk_fma_f32 v[98:99], v[98:99], v[134:135], v[180:181]
	s_waitcnt vmcnt(0)
	v_pk_fma_f32 v[76:77], v[76:77], v[144:145], v[186:187]
	v_pk_fma_f32 v[74:75], v[74:75], v[142:143], v[184:185]
	s_nop 0
	s_and_saveexec_b64 s[0:1], vcc
	s_cbranch_execz .LBB0_925
	s_lshl_b32 s10, s4, 11
	s_add_i32 s10, s5, s10
	v_mul_f32_e32 v130, 0x3c800000, v169
	v_lshl_add_u32 v132, v167, 5, s10
	s_waitcnt lgkmcnt(0)
	v_add_f32_e32 v131, v170, v171
	ds_write_b64 v132, v[130:131]

.LBB0_963:
	s_or_b64 exec, exec, s[2:3]
	s_waitcnt lgkmcnt(0)
	s_barrier
	global_load_dwordx4 v[202:205], v146, s[78:79]
	global_load_dwordx4 v[206:209], v146, s[78:79] offset:64
	global_load_dwordx4 v[210:213], v146, s[78:79] offset:512
	global_load_dwordx4 v[214:217], v146, s[78:79] offset:576
	v_mbcnt_lo_u32_b32 v218, -1, 0
	v_mbcnt_hi_u32_b32 v218, -1, v218
	v_and_b32_e32 v219, 15, v218
	v_lshrrev_b32_e32 v220, 4, v218
	s_lshr_b32 s88, s87, 2
	s_and_b32 s89, s87, 3
	v_and_b32_e32 v221, 3, v219
	v_and_b32_e32 v222, 4, v219
	v_lshl_or_b32 v221, v222, 1, v221
	s_lshl_b32 s90, s89, 3
	v_or_b32_e32 v222, s90, v220
	v_xor_b32_e32 v222, v222, v221
	s_lshl_b32 s90, s88, 6
	v_add_u32_e32 v223, s90, v219
	v_lshlrev_b32_e32 v223, 9, v223
	v_lshl_add_u32 v223, v222, 4, v223
	v_add_u32_e32 v238, 0x4000, v223
	v_add_u32_e32 v239, 0x14000, v223
	s_lshl_b32 s90, s87, 14
	s_add_i32 s90, s90, 0x4000
	v_lshl_add_u32 v240, v218, 4, s90
	v_lshrrev_b32_e32 v224, 5, v218
	v_and_b32_e32 v225, 31, v218
	s_lshl_b32 s90, s87, 5
	v_add_u32_e32 v226, s90, v224
	v_lshlrev_b32_e32 v226, 12, v226
	v_add_u32_e32 v227, 0, v224
	v_and_b32_e32 v228, 3, v227
	v_and_b32_e32 v227, 4, v227
	v_lshl_or_b32 v228, v227, 1, v228
	v_xor_b32_e32 v228, v225, v228
	v_lshl_add_u32 v241, v228, 4, v226
	v_add_u32_e32 v227, 2, v224
	v_and_b32_e32 v228, 3, v227
	v_and_b32_e32 v227, 4, v227
	v_lshl_or_b32 v228, v227, 1, v228
	v_xor_b32_e32 v228, v225, v228
	v_lshl_add_u32 v242, v228, 4, v226
	v_add_u32_e32 v227, 4, v224
	v_and_b32_e32 v228, 3, v227
	v_and_b32_e32 v227, 4, v227
	v_lshl_or_b32 v228, v227, 1, v228
	v_xor_b32_e32 v228, v225, v228
	v_lshl_add_u32 v243, v228, 4, v226
	v_add_u32_e32 v227, 6, v224
	v_and_b32_e32 v228, 3, v227
	v_and_b32_e32 v227, 4, v227
	v_lshl_or_b32 v228, v227, 1, v228
	v_xor_b32_e32 v228, v225, v228
	v_lshl_add_u32 v244, v228, 4, v226
	s_ashr_i32 s84, s64, 2
	s_andn2_b32 s84, s84, 31
	s_lshl_b32 s85, s64, 2
	s_and_b32 s85, s85, 28
	s_or_b32 s84, s84, s85
	s_bfe_u32 s85, s64, 0x20005
	s_or_b32 s84, s84, s85
	s_bfe_u32 s85, s64, 0x20003
	s_lshl_b32 s84, s84, 20
	s_lshl_b32 s85, s85, 10
	s_add_u32 s86, s84, s85
	s_add_u32 s84, s80, s86
	s_addc_u32 s85, s81, 0
	v_lshl_add_u32 v158, v166, 3, 0
	v_lshl_add_u64 v[130:131], v[144:145], 2, s[80:81]
	v_lshl_add_u64 v[138:139], v[138:139], 2, s[80:81]
	v_lshl_add_u64 v[136:137], v[136:137], 2, s[80:81]
	v_lshl_add_u64 v[154:155], v[132:133], 2, s[80:81]
	v_lshl_add_u64 v[156:157], v[0:1], 2, s[80:81]
	v_add_u32_e32 v144, 0x2000, v158
	v_lshl_add_u64 v[0:1], v[130:131], 0, v[146:147]
	v_lshl_add_u64 v[130:131], v[138:139], 0, v[146:147]
	v_lshl_add_u64 v[132:133], v[136:137], 0, v[146:147]
	v_lshl_add_u64 v[136:137], v[154:155], 0, v[146:147]
	v_lshl_add_u64 v[138:139], v[156:157], 0, v[146:147]
	ds_read2_b64 v[154:157], v144 offset1:16
	v_or_b32_e32 v149, v165, v164
	ds_read2_b64 v[158:161], v144 offset0:32 offset1:48
	ds_read2_b64 v[162:165], v144 offset0:128 offset1:144
	ds_read2_b64 v[166:169], v144 offset0:160 offset1:176
	s_cmpk_lg_i32 s53, 0x100
	s_waitcnt lgkmcnt(0)
	v_cmp_ne_u32_e32 vcc, 0, v148
	s_cselect_b64 s[2:3], -1, 0
	v_cmp_ne_u32_e64 s[0:1], 0, v149
	s_or_b64 s[2:3], vcc, s[2:3]
	v_pk_mul_f32 v[66:67], v[66:67], v[154:155] op_sel:[0,1]
	v_pk_mul_f32 v[68:69], v[68:69], v[154:155] op_sel:[0,1]
	v_mov_b32_e32 v148, 0x7fc00000
	v_pk_mul_f32 v[78:79], v[78:79], v[156:157] op_sel:[0,1]
	v_pk_mul_f32 v[80:81], v[80:81], v[156:157] op_sel:[0,1]
	v_pk_mul_f32 v[90:91], v[90:91], v[158:159] op_sel:[0,1]
	v_pk_mul_f32 v[92:93], v[92:93], v[158:159] op_sel:[0,1]
	v_pk_mul_f32 v[102:103], v[102:103], v[160:161] op_sel:[0,1]
	v_pk_mul_f32 v[104:105], v[104:105], v[160:161] op_sel:[0,1]
	v_pk_mul_f32 v[106:107], v[106:107], v[162:163] op_sel:[0,1]
	v_pk_mul_f32 v[108:109], v[108:109], v[162:163] op_sel:[0,1]
	v_pk_mul_f32 v[118:119], v[118:119], v[164:165] op_sel:[0,1]
	v_pk_mul_f32 v[120:121], v[120:121], v[164:165] op_sel:[0,1]
	s_or_b64 vcc, s[2:3], s[0:1]
	v_lshl_add_u64 v[134:135], v[134:135], 2, s[80:81]
	v_lshl_add_u64 v[134:135], v[134:135], 0, v[146:147]
	s_waitcnt vmcnt(0)
	v_pk_mul_f32 v[68:69], v[204:205], v[68:69]
	v_pk_mul_f32 v[66:67], v[202:203], v[66:67]
	v_pk_mul_f32 v[80:81], v[204:205], v[80:81]
	v_pk_mul_f32 v[78:79], v[202:203], v[78:79]
	v_pk_mul_f32 v[92:93], v[204:205], v[92:93]
	v_pk_mul_f32 v[90:91], v[202:203], v[90:91]
	v_pk_mul_f32 v[104:105], v[204:205], v[104:105]
	v_pk_mul_f32 v[102:103], v[202:203], v[102:103]
	v_pk_mul_f32 v[108:109], v[204:205], v[108:109]
	v_pk_mul_f32 v[106:107], v[202:203], v[106:107]
	v_pk_mul_f32 v[120:121], v[204:205], v[120:121]
	v_pk_mul_f32 v[118:119], v[202:203], v[118:119]
	v_cndmask_b32_e32 v67, v67, v148, vcc
	v_cndmask_b32_e32 v66, v66, v148, vcc
	v_cndmask_b32_e32 v69, v69, v148, vcc
	v_cndmask_b32_e32 v68, v68, v148, vcc
	v_cndmask_b32_e32 v79, v79, v148, vcc
	v_cndmask_b32_e32 v78, v78, v148, vcc
	v_cndmask_b32_e32 v81, v81, v148, vcc
	v_cndmask_b32_e32 v80, v80, v148, vcc
	v_cndmask_b32_e32 v91, v91, v148, vcc
	v_cndmask_b32_e32 v90, v90, v148, vcc
	v_cndmask_b32_e32 v93, v93, v148, vcc
	v_cndmask_b32_e32 v92, v92, v148, vcc
	v_cndmask_b32_e32 v103, v103, v148, vcc
	v_cndmask_b32_e32 v102, v102, v148, vcc
	v_cndmask_b32_e32 v105, v105, v148, vcc
	v_cndmask_b32_e32 v104, v104, v148, vcc
	v_cndmask_b32_e32 v107, v107, v148, vcc
	v_cndmask_b32_e32 v106, v106, v148, vcc
	v_cndmask_b32_e32 v109, v109, v148, vcc
	v_cndmask_b32_e32 v108, v108, v148, vcc
	v_cndmask_b32_e32 v119, v119, v148, vcc
	v_cndmask_b32_e32 v118, v118, v148, vcc
	v_cndmask_b32_e32 v121, v121, v148, vcc
	v_cndmask_b32_e32 v120, v120, v148, vcc
	ds_write_b128 v238, v[66:69]
	ds_write_b128 v238, v[78:81] offset:8192
	ds_write_b128 v238, v[90:93] offset:16384
	ds_write_b128 v238, v[102:105] offset:24576
	ds_write_b128 v239, v[106:109]
	ds_write_b128 v239, v[118:121] offset:8192
	v_pk_mul_f32 v[66:67], v[126:127], v[166:167] op_sel:[0,1]
	v_pk_mul_f32 v[68:69], v[128:129], v[166:167] op_sel:[0,1]
	v_pk_mul_f32 v[66:67], v[202:203], v[66:67]
	v_pk_mul_f32 v[68:69], v[204:205], v[68:69]
	v_cndmask_b32_e32 v79, v67, v148, vcc
	v_cndmask_b32_e32 v78, v66, v148, vcc
	v_lshl_add_u64 v[66:67], v[142:143], 2, s[80:81]
	v_cndmask_b32_e32 v81, v69, v148, vcc
	v_cndmask_b32_e32 v80, v68, v148, vcc
	v_lshl_add_u64 v[66:67], v[66:67], 0, v[146:147]
	v_pk_mul_f32 v[68:69], v[122:123], v[168:169] op_sel:[0,1]
	ds_write_b128 v239, v[78:81] offset:16384
	v_pk_mul_f32 v[68:69], v[202:203], v[68:69]
	s_nop 0
	v_pk_mul_f32 v[78:79], v[124:125], v[168:169] op_sel:[0,1]
	s_nop 0
	v_pk_mul_f32 v[80:81], v[204:205], v[78:79]
	v_cndmask_b32_e32 v79, v69, v148, vcc
	v_cndmask_b32_e32 v78, v68, v148, vcc
	v_lshl_add_u64 v[68:69], v[140:141], 2, s[80:81]
	v_cndmask_b32_e32 v81, v81, v148, vcc
	v_cndmask_b32_e32 v80, v80, v148, vcc
	v_lshl_add_u64 v[68:69], v[68:69], 0, v[146:147]
	ds_write_b128 v239, v[78:81] offset:24576
	ds_read2_b64 v[90:93], v144 offset1:16
	ds_read2_b64 v[102:105], v144 offset0:32 offset1:48
	ds_read2_b64 v[106:109], v144 offset0:128 offset1:144
	ds_read2_b64 v[118:121], v144 offset0:160 offset1:176
	s_waitcnt lgkmcnt(3)
	v_pk_mul_f32 v[38:39], v[38:39], v[90:91] op_sel:[0,1]
	v_pk_mul_f32 v[40:41], v[40:41], v[90:91] op_sel:[0,1]
	v_pk_mul_f32 v[46:47], v[46:47], v[92:93] op_sel:[0,1]
	v_pk_mul_f32 v[48:49], v[48:49], v[92:93] op_sel:[0,1]
	s_waitcnt lgkmcnt(2)
	v_pk_mul_f32 v[58:59], v[58:59], v[102:103] op_sel:[0,1]
	v_pk_mul_f32 v[60:61], v[60:61], v[102:103] op_sel:[0,1]
	v_pk_mul_f32 v[70:71], v[70:71], v[104:105] op_sel:[0,1]
	v_pk_mul_f32 v[72:73], v[72:73], v[104:105] op_sel:[0,1]
	s_waitcnt lgkmcnt(1)
	v_pk_mul_f32 v[82:83], v[82:83], v[106:107] op_sel:[0,1]
	v_pk_mul_f32 v[84:85], v[84:85], v[106:107] op_sel:[0,1]
	v_pk_mul_f32 v[90:91], v[94:95], v[108:109] op_sel:[0,1]
	v_pk_mul_f32 v[92:93], v[96:97], v[108:109] op_sel:[0,1]
	s_waitcnt lgkmcnt(0)
	v_pk_mul_f32 v[94:95], v[110:111], v[118:119] op_sel:[0,1]
	v_pk_mul_f32 v[96:97], v[112:113], v[118:119] op_sel:[0,1]
	v_pk_mul_f32 v[40:41], v[208:209], v[40:41]
	v_pk_mul_f32 v[38:39], v[206:207], v[38:39]
	v_pk_mul_f32 v[48:49], v[208:209], v[48:49]
	v_pk_mul_f32 v[46:47], v[206:207], v[46:47]
	v_pk_mul_f32 v[60:61], v[208:209], v[60:61]
	v_pk_mul_f32 v[58:59], v[206:207], v[58:59]
	v_pk_mul_f32 v[72:73], v[208:209], v[72:73]
	v_pk_mul_f32 v[70:71], v[206:207], v[70:71]
	v_pk_mul_f32 v[84:85], v[208:209], v[84:85]
	v_pk_mul_f32 v[82:83], v[206:207], v[82:83]
	v_pk_mul_f32 v[92:93], v[208:209], v[92:93]
	v_pk_mul_f32 v[90:91], v[206:207], v[90:91]
	v_cndmask_b32_e32 v39, v39, v148, vcc
	v_cndmask_b32_e32 v38, v38, v148, vcc
	v_cndmask_b32_e32 v41, v41, v148, vcc
	v_cndmask_b32_e32 v40, v40, v148, vcc
	v_cndmask_b32_e32 v47, v47, v148, vcc
	v_cndmask_b32_e32 v46, v46, v148, vcc
	v_cndmask_b32_e32 v49, v49, v148, vcc
	v_cndmask_b32_e32 v48, v48, v148, vcc
	v_cndmask_b32_e32 v59, v59, v148, vcc
	v_cndmask_b32_e32 v58, v58, v148, vcc
	v_cndmask_b32_e32 v61, v61, v148, vcc
	v_cndmask_b32_e32 v60, v60, v148, vcc
	v_cndmask_b32_e32 v71, v71, v148, vcc
	v_cndmask_b32_e32 v70, v70, v148, vcc
	v_cndmask_b32_e32 v73, v73, v148, vcc
	v_cndmask_b32_e32 v72, v72, v148, vcc
	v_cndmask_b32_e32 v83, v83, v148, vcc
	v_cndmask_b32_e32 v82, v82, v148, vcc
	v_cndmask_b32_e32 v85, v85, v148, vcc
	v_cndmask_b32_e32 v84, v84, v148, vcc
	v_cndmask_b32_e32 v91, v91, v148, vcc
	v_cndmask_b32_e32 v90, v90, v148, vcc
	v_cndmask_b32_e32 v93, v93, v148, vcc
	v_cndmask_b32_e32 v92, v92, v148, vcc
	ds_write_b128 v238, v[38:41] offset:64
	ds_write_b128 v238, v[46:49] offset:8256
	ds_write_b128 v238, v[58:61] offset:16448
	ds_write_b128 v238, v[70:73] offset:24640
	ds_write_b128 v239, v[82:85] offset:64
	ds_write_b128 v239, v[90:93] offset:8256
	v_pk_mul_f32 v[40:41], v[208:209], v[96:97]
	v_pk_mul_f32 v[38:39], v[206:207], v[94:95]
	v_cndmask_b32_e32 v41, v41, v148, vcc
	v_cndmask_b32_e32 v39, v39, v148, vcc
	v_cndmask_b32_e32 v38, v38, v148, vcc
	v_cndmask_b32_e32 v40, v40, v148, vcc
	ds_write_b128 v239, v[38:41] offset:16448
	s_nop 1
	v_pk_mul_f32 v[38:39], v[114:115], v[120:121] op_sel:[0,1]
	v_pk_mul_f32 v[40:41], v[116:117], v[120:121] op_sel:[0,1]
	v_pk_mul_f32 v[38:39], v[206:207], v[38:39]
	v_pk_mul_f32 v[40:41], v[208:209], v[40:41]
	v_cndmask_b32_e32 v39, v39, v148, vcc
	v_cndmask_b32_e32 v38, v38, v148, vcc
	v_cndmask_b32_e32 v41, v41, v148, vcc
	v_cndmask_b32_e32 v40, v40, v148, vcc
	ds_write_b128 v239, v[38:41] offset:24640
	s_waitcnt lgkmcnt(0)
	s_barrier
	ds_read_b128 v[38:41], v240
	ds_read_b128 v[46:49], v240 offset:1024
	ds_read_b128 v[58:61], v240 offset:2048
	ds_read_b128 v[70:73], v240 offset:3072
	ds_read_b128 v[78:81], v240 offset:4096
	ds_read_b128 v[82:85], v240 offset:5120
	ds_read_b128 v[90:93], v240 offset:6144
	ds_read_b128 v[94:97], v240 offset:7168
	ds_read_b128 v[102:105], v240 offset:8192
	ds_read_b128 v[106:109], v240 offset:9216
	ds_read_b128 v[110:113], v240 offset:10240
	ds_read_b128 v[114:117], v240 offset:11264
	ds_read_b128 v[118:121], v240 offset:12288
	ds_read_b128 v[122:125], v240 offset:13312
	ds_read_b128 v[126:129], v240 offset:14336
	ds_read_b128 v[140:143], v240 offset:15360
	s_waitcnt lgkmcnt(0)
	s_barrier
	v_add_u32_e32 v245, 0x0, v241
	global_store_dwordx4 v245, v[38:41], s[84:85]
	v_add_u32_e32 v245, 0x2000, v242
	global_store_dwordx4 v245, v[46:49], s[84:85]
	v_add_u32_e32 v245, 0x4000, v243
	global_store_dwordx4 v245, v[58:61], s[84:85]
	v_add_u32_e32 v245, 0x6000, v244
	global_store_dwordx4 v245, v[70:73], s[84:85]
	v_add_u32_e32 v245, 0x8000, v241
	global_store_dwordx4 v245, v[78:81], s[84:85]
	v_add_u32_e32 v245, 0xa000, v242
	global_store_dwordx4 v245, v[82:85], s[84:85]
	v_add_u32_e32 v245, 0xc000, v243
	global_store_dwordx4 v245, v[90:93], s[84:85]
	v_add_u32_e32 v245, 0xe000, v244
	global_store_dwordx4 v245, v[94:97], s[84:85]
	v_add_u32_e32 v245, 0x10000, v241
	global_store_dwordx4 v245, v[102:105], s[84:85]
	v_add_u32_e32 v245, 0x12000, v242
	global_store_dwordx4 v245, v[106:109], s[84:85]
	v_add_u32_e32 v245, 0x14000, v243
	global_store_dwordx4 v245, v[110:113], s[84:85]
	v_add_u32_e32 v245, 0x16000, v244
	global_store_dwordx4 v245, v[114:117], s[84:85]
	v_add_u32_e32 v245, 0x18000, v241
	global_store_dwordx4 v245, v[118:121], s[84:85]
	v_add_u32_e32 v245, 0x1a000, v242
	global_store_dwordx4 v245, v[122:125], s[84:85]
	v_add_u32_e32 v245, 0x1c000, v243
	global_store_dwordx4 v245, v[126:129], s[84:85]
	v_add_u32_e32 v245, 0x1e000, v244
	global_store_dwordx4 v245, v[140:143], s[84:85]
	ds_read2_b64 v[46:49], v144 offset1:16
	ds_read2_b64 v[58:61], v144 offset0:32 offset1:48
	ds_read2_b64 v[70:73], v144 offset0:128 offset1:144
	ds_read2_b64 v[78:81], v144 offset0:160 offset1:176
	s_waitcnt lgkmcnt(3)
	v_pk_mul_f32 v[14:15], v[14:15], v[46:47] op_sel:[0,1]
	v_pk_mul_f32 v[16:17], v[16:17], v[46:47] op_sel:[0,1]
	v_pk_mul_f32 v[22:23], v[22:23], v[48:49] op_sel:[0,1]
	v_pk_mul_f32 v[24:25], v[24:25], v[48:49] op_sel:[0,1]
	s_waitcnt lgkmcnt(2)
	v_pk_mul_f32 v[30:31], v[30:31], v[58:59] op_sel:[0,1]
	v_pk_mul_f32 v[32:33], v[32:33], v[58:59] op_sel:[0,1]
	v_pk_mul_f32 v[42:43], v[42:43], v[60:61] op_sel:[0,1]
	v_pk_mul_f32 v[44:45], v[44:45], v[60:61] op_sel:[0,1]
	s_waitcnt lgkmcnt(1)
	v_pk_mul_f32 v[46:47], v[50:51], v[70:71] op_sel:[0,1]
	v_pk_mul_f32 v[48:49], v[52:53], v[70:71] op_sel:[0,1]
	v_pk_mul_f32 v[50:51], v[62:63], v[72:73] op_sel:[0,1]
	v_pk_mul_f32 v[52:53], v[64:65], v[72:73] op_sel:[0,1]
	s_waitcnt lgkmcnt(0)
	v_pk_mul_f32 v[58:59], v[86:87], v[78:79] op_sel:[0,1]
	v_pk_mul_f32 v[60:61], v[88:89], v[78:79] op_sel:[0,1]
	v_pk_mul_f32 v[16:17], v[212:213], v[16:17]
	v_pk_mul_f32 v[14:15], v[210:211], v[14:15]
	v_pk_mul_f32 v[24:25], v[212:213], v[24:25]
	v_pk_mul_f32 v[22:23], v[210:211], v[22:23]
	v_pk_mul_f32 v[32:33], v[212:213], v[32:33]
	v_pk_mul_f32 v[30:31], v[210:211], v[30:31]
	v_pk_mul_f32 v[44:45], v[212:213], v[44:45]
	v_pk_mul_f32 v[42:43], v[210:211], v[42:43]
	v_pk_mul_f32 v[48:49], v[212:213], v[48:49]
	v_pk_mul_f32 v[46:47], v[210:211], v[46:47]
	v_pk_mul_f32 v[52:53], v[212:213], v[52:53]
	v_pk_mul_f32 v[50:51], v[210:211], v[50:51]
	v_pk_mul_f32 v[60:61], v[212:213], v[60:61]
	v_pk_mul_f32 v[58:59], v[210:211], v[58:59]
	v_cndmask_b32_e32 v15, v15, v148, vcc
	v_cndmask_b32_e32 v14, v14, v148, vcc
	v_cndmask_b32_e32 v17, v17, v148, vcc
	v_cndmask_b32_e32 v16, v16, v148, vcc
	v_cndmask_b32_e32 v23, v23, v148, vcc
	v_cndmask_b32_e32 v22, v22, v148, vcc
	v_cndmask_b32_e32 v25, v25, v148, vcc
	v_cndmask_b32_e32 v24, v24, v148, vcc
	v_cndmask_b32_e32 v31, v31, v148, vcc
	v_cndmask_b32_e32 v30, v30, v148, vcc
	v_cndmask_b32_e32 v33, v33, v148, vcc
	v_cndmask_b32_e32 v32, v32, v148, vcc
	v_cndmask_b32_e32 v43, v43, v148, vcc
	v_cndmask_b32_e32 v42, v42, v148, vcc
	v_cndmask_b32_e32 v45, v45, v148, vcc
	v_cndmask_b32_e32 v44, v44, v148, vcc
	v_cndmask_b32_e32 v47, v47, v148, vcc
	v_cndmask_b32_e32 v46, v46, v148, vcc
	v_cndmask_b32_e32 v49, v49, v148, vcc
	v_cndmask_b32_e32 v48, v48, v148, vcc
	v_cndmask_b32_e32 v51, v51, v148, vcc
	v_cndmask_b32_e32 v50, v50, v148, vcc
	v_cndmask_b32_e32 v53, v53, v148, vcc
	v_cndmask_b32_e32 v52, v52, v148, vcc
	v_cndmask_b32_e32 v59, v59, v148, vcc
	v_cndmask_b32_e32 v58, v58, v148, vcc
	v_cndmask_b32_e32 v61, v61, v148, vcc
	v_cndmask_b32_e32 v60, v60, v148, vcc
	ds_write_b128 v238, v[14:17]
	ds_write_b128 v238, v[22:25] offset:8192
	ds_write_b128 v238, v[30:33] offset:16384
	ds_write_b128 v238, v[42:45] offset:24576
	ds_write_b128 v239, v[46:49]
	ds_write_b128 v239, v[50:53] offset:8192
	ds_write_b128 v239, v[58:61] offset:16384
	v_pk_mul_f32 v[14:15], v[98:99], v[80:81] op_sel:[0,1]
	v_pk_mul_f32 v[16:17], v[100:101], v[80:81] op_sel:[0,1]
	v_pk_mul_f32 v[14:15], v[210:211], v[14:15]
	v_pk_mul_f32 v[16:17], v[212:213], v[16:17]
	v_cndmask_b32_e32 v15, v15, v148, vcc
	v_cndmask_b32_e32 v14, v14, v148, vcc
	v_cndmask_b32_e32 v17, v17, v148, vcc
	v_cndmask_b32_e32 v16, v16, v148, vcc
	ds_write_b128 v239, v[14:17] offset:24576
	ds_read2_b64 v[22:25], v144 offset1:16
	ds_read2_b64 v[30:33], v144 offset0:32 offset1:48
	ds_read2_b64 v[38:41], v144 offset0:128 offset1:144
	ds_read2_b64 v[42:45], v144 offset0:160 offset1:176
	s_waitcnt lgkmcnt(3)
	v_pk_mul_f32 v[2:3], v[2:3], v[22:23] op_sel:[0,1]
	v_pk_mul_f32 v[4:5], v[4:5], v[22:23] op_sel:[0,1]
	v_pk_mul_f32 v[6:7], v[6:7], v[24:25] op_sel:[0,1]
	v_pk_mul_f32 v[8:9], v[8:9], v[24:25] op_sel:[0,1]
	s_waitcnt lgkmcnt(2)
	v_pk_mul_f32 v[10:11], v[10:11], v[30:31] op_sel:[0,1]
	v_pk_mul_f32 v[12:13], v[12:13], v[30:31] op_sel:[0,1]
	v_pk_mul_f32 v[18:19], v[18:19], v[32:33] op_sel:[0,1]
	v_pk_mul_f32 v[20:21], v[20:21], v[32:33] op_sel:[0,1]
	s_waitcnt lgkmcnt(1)
	v_pk_mul_f32 v[22:23], v[26:27], v[38:39] op_sel:[0,1]
	v_pk_mul_f32 v[24:25], v[28:29], v[38:39] op_sel:[0,1]
	v_pk_mul_f32 v[26:27], v[34:35], v[40:41] op_sel:[0,1]
	v_pk_mul_f32 v[28:29], v[36:37], v[40:41] op_sel:[0,1]
	s_waitcnt lgkmcnt(0)
	v_pk_mul_f32 v[30:31], v[54:55], v[42:43] op_sel:[0,1]
	v_pk_mul_f32 v[32:33], v[56:57], v[42:43] op_sel:[0,1]
	v_pk_mul_f32 v[34:35], v[74:75], v[44:45] op_sel:[0,1]
	v_pk_mul_f32 v[36:37], v[76:77], v[44:45] op_sel:[0,1]
	v_pk_mul_f32 v[4:5], v[216:217], v[4:5]
	v_pk_mul_f32 v[2:3], v[214:215], v[2:3]
	v_pk_mul_f32 v[20:21], v[216:217], v[20:21]
	v_pk_mul_f32 v[18:19], v[214:215], v[18:19]
	v_pk_mul_f32 v[24:25], v[216:217], v[24:25]
	v_pk_mul_f32 v[22:23], v[214:215], v[22:23]
	v_pk_mul_f32 v[28:29], v[216:217], v[28:29]
	v_pk_mul_f32 v[26:27], v[214:215], v[26:27]
	v_pk_mul_f32 v[32:33], v[216:217], v[32:33]
	v_pk_mul_f32 v[30:31], v[214:215], v[30:31]
	v_pk_mul_f32 v[36:37], v[216:217], v[36:37]
	v_pk_mul_f32 v[34:35], v[214:215], v[34:35]
	v_pk_mul_f32 v[8:9], v[216:217], v[8:9]
	v_pk_mul_f32 v[6:7], v[214:215], v[6:7]
	v_pk_mul_f32 v[12:13], v[216:217], v[12:13]
	v_pk_mul_f32 v[10:11], v[214:215], v[10:11]
	v_cndmask_b32_e32 v3, v3, v148, vcc
	v_cndmask_b32_e32 v2, v2, v148, vcc
	v_cndmask_b32_e32 v5, v5, v148, vcc
	v_cndmask_b32_e32 v4, v4, v148, vcc
	v_cndmask_b32_e32 v15, v19, v148, vcc
	v_cndmask_b32_e32 v14, v18, v148, vcc
	v_cndmask_b32_e32 v17, v21, v148, vcc
	v_cndmask_b32_e32 v16, v20, v148, vcc
	v_cndmask_b32_e32 v19, v23, v148, vcc
	v_cndmask_b32_e32 v18, v22, v148, vcc
	v_cndmask_b32_e32 v21, v25, v148, vcc
	v_cndmask_b32_e32 v20, v24, v148, vcc
	v_cndmask_b32_e32 v23, v27, v148, vcc
	v_cndmask_b32_e32 v22, v26, v148, vcc
	v_cndmask_b32_e32 v25, v29, v148, vcc
	v_cndmask_b32_e32 v24, v28, v148, vcc
	v_cndmask_b32_e32 v27, v31, v148, vcc
	v_cndmask_b32_e32 v26, v30, v148, vcc
	v_cndmask_b32_e32 v29, v33, v148, vcc
	v_cndmask_b32_e32 v28, v32, v148, vcc
	v_cndmask_b32_e32 v31, v35, v148, vcc
	v_cndmask_b32_e32 v30, v34, v148, vcc
	v_cndmask_b32_e32 v33, v37, v148, vcc
	v_cndmask_b32_e32 v32, v36, v148, vcc
	v_cndmask_b32_e32 v7, v7, v148, vcc
	v_cndmask_b32_e32 v6, v6, v148, vcc
	v_cndmask_b32_e32 v9, v9, v148, vcc
	v_cndmask_b32_e32 v8, v8, v148, vcc
	v_cndmask_b32_e32 v11, v11, v148, vcc
	v_cndmask_b32_e32 v10, v10, v148, vcc
	v_cndmask_b32_e32 v13, v13, v148, vcc
	v_cndmask_b32_e32 v12, v12, v148, vcc
	ds_write_b128 v238, v[2:5] offset:64
	ds_write_b128 v238, v[6:9] offset:8256
	ds_write_b128 v238, v[10:13] offset:16448
	ds_write_b128 v238, v[14:17] offset:24640
	ds_write_b128 v239, v[18:21] offset:64
	ds_write_b128 v239, v[22:25] offset:8256
	ds_write_b128 v239, v[26:29] offset:16448
	ds_write_b128 v239, v[30:33] offset:24640
	s_waitcnt lgkmcnt(0)
	s_barrier
	ds_read_b128 v[38:41], v240
	ds_read_b128 v[46:49], v240 offset:1024
	ds_read_b128 v[58:61], v240 offset:2048
	ds_read_b128 v[70:73], v240 offset:3072
	ds_read_b128 v[78:81], v240 offset:4096
	ds_read_b128 v[82:85], v240 offset:5120
	ds_read_b128 v[90:93], v240 offset:6144
	ds_read_b128 v[94:97], v240 offset:7168
	ds_read_b128 v[102:105], v240 offset:8192
	ds_read_b128 v[106:109], v240 offset:9216
	ds_read_b128 v[110:113], v240 offset:10240
	ds_read_b128 v[114:117], v240 offset:11264
	ds_read_b128 v[118:121], v240 offset:12288
	ds_read_b128 v[122:125], v240 offset:13312
	ds_read_b128 v[126:129], v240 offset:14336
	ds_read_b128 v[140:143], v240 offset:15360
	s_waitcnt lgkmcnt(0)
	s_barrier
	v_add_u32_e32 v245, 0x0, v241
	global_store_dwordx4 v245, v[38:41], s[84:85] offset:512
	v_add_u32_e32 v245, 0x2000, v242
	global_store_dwordx4 v245, v[46:49], s[84:85] offset:512
	v_add_u32_e32 v245, 0x4000, v243
	global_store_dwordx4 v245, v[58:61], s[84:85] offset:512
	v_add_u32_e32 v245, 0x6000, v244
	global_store_dwordx4 v245, v[70:73], s[84:85] offset:512
	v_add_u32_e32 v245, 0x8000, v241
	global_store_dwordx4 v245, v[78:81], s[84:85] offset:512
	v_add_u32_e32 v245, 0xa000, v242
	global_store_dwordx4 v245, v[82:85], s[84:85] offset:512
	v_add_u32_e32 v245, 0xc000, v243
	global_store_dwordx4 v245, v[90:93], s[84:85] offset:512
	v_add_u32_e32 v245, 0xe000, v244
	global_store_dwordx4 v245, v[94:97], s[84:85] offset:512
	v_add_u32_e32 v245, 0x10000, v241
	global_store_dwordx4 v245, v[102:105], s[84:85] offset:512
	v_add_u32_e32 v245, 0x12000, v242
	global_store_dwordx4 v245, v[106:109], s[84:85] offset:512
	v_add_u32_e32 v245, 0x14000, v243
	global_store_dwordx4 v245, v[110:113], s[84:85] offset:512
	v_add_u32_e32 v245, 0x16000, v244
	global_store_dwordx4 v245, v[114:117], s[84:85] offset:512
	v_add_u32_e32 v245, 0x18000, v241
	global_store_dwordx4 v245, v[118:121], s[84:85] offset:512
	v_add_u32_e32 v245, 0x1a000, v242
	global_store_dwordx4 v245, v[122:125], s[84:85] offset:512
	v_add_u32_e32 v245, 0x1c000, v243
	global_store_dwordx4 v245, v[126:129], s[84:85] offset:512
	v_add_u32_e32 v245, 0x1e000, v244
	global_store_dwordx4 v245, v[140:143], s[84:85] offset:512
	s_endpgm
